# P6: per-XCD ticket queues (K/V tile L2 reuse), counted vmcnt on K/V staging, static prio for waves 0-3, batched lru_final loads
# speedup vs baseline: 1.0314x; 1.0132x over previous
.LBB0_1297:
.LBB0_1298:
	s_cmp_lt_i32 s14, 7
	s_cselect_b64 s[0:1], -1, 0
	s_cmp_gt_i32 s15, 6
	s_cselect_b64 s[4:5], -1, 0
	s_and_b64 s[0:1], s[0:1], s[4:5]
	s_andn2_b64 vcc, exec, s[0:1]
	s_cbranch_vccnz .LBB0_1473
	v_readfirstlane_b32 s62, v0
	s_nop 3
	s_lshr_b32 s62, s62, 8
	s_cmp_eq_u32 s62, 0
	s_cbranch_scc0 .Lp6_noprio
	s_setprio 1
.Lp6_noprio:
	v_readlane_b32 s48, v244, 36
	v_and_b32_e32 v1, 63, v0
	v_readlane_b32 s49, v244, 37
	v_lshlrev_b32_e32 v1, 2, v1
	v_readlane_b32 s50, v244, 38
	v_readlane_b32 s51, v244, 39
	v_readlane_b32 s52, v244, 40
	v_readlane_b32 s53, v244, 41
	v_readlane_b32 s54, v244, 42
	v_readlane_b32 s55, v244, 43
	v_readlane_b32 s56, v244, 44
	v_readlane_b32 s57, v244, 45
	s_mov_b64 s[4:5], s[48:49]
	s_mov_b64 s[6:7], s[50:51]
	s_mov_b64 s[8:9], s[52:53]
	s_mov_b64 s[10:11], s[54:55]
	global_load_dword v2, v1, s[4:5]
	global_load_dword v3, v1, s[6:7]
	s_waitcnt lgkmcnt(0)
	global_load_dword v4, v1, s[8:9]
	global_load_dword v5, v1, s[10:11]
	v_mbcnt_lo_u32_b32 v1, -1, 0
	s_waitcnt vmcnt(0)
	v_mbcnt_hi_u32_b32 v6, -1, v1
	v_and_b32_e32 v7, 64, v6
	v_xor_b32_e32 v1, 32, v6
	v_add_u32_e32 v13, 64, v7
	v_cmp_lt_i32_e32 vcc, v1, v13
	v_xor_b32_e32 v8, 16, v6
	v_xor_b32_e32 v9, 8, v6
	v_cndmask_b32_e32 v1, v6, v1, vcc
	v_lshlrev_b32_e32 v1, 2, v1
	v_cmp_lt_i32_e32 vcc, v8, v13
	v_xor_b32_e32 v10, 4, v6
	v_xor_b32_e32 v11, 2, v6
	v_cndmask_b32_e32 v8, v6, v8, vcc
	v_lshlrev_b32_e32 v202, 2, v8
	v_cmp_lt_i32_e32 vcc, v9, v13
	v_xor_b32_e32 v12, 1, v6
	s_cmp_gt_i32 s2, 3
	v_readlane_b32 s58, v244, 46
	v_readlane_b32 s59, v244, 47
	v_readlane_b32 s60, v244, 48
	v_readlane_b32 s61, v244, 49
	v_readlane_b32 s62, v244, 50
	v_readlane_b32 s63, v244, 51
	s_mov_b64 s[12:13], s[56:57]
	v_mul_f32_e32 v14, v2, v3
	ds_bpermute_b32 v14, v1, v14
	v_mul_f32_e32 v15, v4, v5
	ds_bpermute_b32 v15, v1, v15
	s_waitcnt lgkmcnt(1)
	v_fmac_f32_e32 v14, v2, v3
	ds_bpermute_b32 v2, v202, v14
	s_waitcnt lgkmcnt(1)
	v_fmac_f32_e32 v15, v4, v5
	ds_bpermute_b32 v3, v202, v15
	v_cndmask_b32_e32 v4, v6, v9, vcc
	v_lshlrev_b32_e32 v203, 2, v4
	s_waitcnt lgkmcnt(1)
	v_add_f32_e32 v2, v14, v2
	ds_bpermute_b32 v4, v203, v2
	s_waitcnt lgkmcnt(1)
	v_add_f32_e32 v3, v15, v3
	ds_bpermute_b32 v5, v203, v3
	v_cmp_lt_i32_e32 vcc, v10, v13
	s_waitcnt lgkmcnt(1)
	v_add_f32_e32 v2, v2, v4
	v_cndmask_b32_e32 v8, v6, v10, vcc
	v_lshlrev_b32_e32 v204, 2, v8
	s_waitcnt lgkmcnt(0)
	v_add_f32_e32 v3, v3, v5
	ds_bpermute_b32 v4, v204, v2
	ds_bpermute_b32 v5, v204, v3
	v_cmp_lt_i32_e32 vcc, v11, v13
	s_waitcnt lgkmcnt(1)
	v_add_f32_e32 v2, v2, v4
	v_cndmask_b32_e32 v8, v6, v11, vcc
	v_lshlrev_b32_e32 v205, 2, v8
	s_waitcnt lgkmcnt(0)
	v_add_f32_e32 v3, v3, v5
	ds_bpermute_b32 v4, v205, v2
	ds_bpermute_b32 v5, v205, v3
	v_cmp_lt_i32_e32 vcc, v12, v13
	s_waitcnt lgkmcnt(1)
	v_add_f32_e32 v9, v2, v4
	v_cndmask_b32_e32 v8, v6, v12, vcc
	v_lshlrev_b32_e32 v206, 2, v8
	s_waitcnt lgkmcnt(0)
	v_add_f32_e32 v8, v3, v5
	ds_bpermute_b32 v11, v206, v9
	ds_bpermute_b32 v10, v206, v8
	s_cbranch_scc1 .LBB0_1306
	s_ashr_i32 s3, s2, 31
	s_lshl_b64 s[0:1], s[2:3], 18
	v_mov_b32_e32 v2, v0
	s_add_u32 s0, s86, s0
	s_addc_u32 s1, s87, s1
	v_ashrrev_i32_e32 v3, 31, v2
	v_lshl_add_u64 v[4:5], v[2:3], 2, s[0:1]
	s_mov_b64 s[0:1], 0x1e193900
	v_lshl_add_u64 v[4:5], v[4:5], 0, s[0:1]
	v_mov_b32_e32 v12, 0
	s_mov_b32 s4, -16
	s_mov_b64 s[0:1], 0x8000

.LBB0_1306:
	s_and_b32 s62, s80, 7
	s_lshl_b32 s62, s62, 6
	s_add_u32 s8, s86, 0x1e28f900
	s_addc_u32 s9, s87, 0
	s_add_u32 s8, s8, s62
	s_addc_u32 s9, s9, 0
	s_and_saveexec_b64 s[0:1], s[82:83]
	s_cbranch_execz .LBB0_1310
	s_mov_b64 s[6:7], exec
	v_mbcnt_lo_u32_b32 v2, s6, 0
	v_mbcnt_hi_u32_b32 v2, s7, v2
	v_cmp_eq_u32_e32 vcc, 0, v2
	s_and_saveexec_b64 s[4:5], vcc
	s_cbranch_execz .LBB0_1309
	s_bcnt1_i32_b64 s3, s[6:7]
	v_mov_b32_e32 v3, 0
	v_mov_b32_e32 v4, s3
	global_atomic_add v3, v3, v4, s[8:9] sc0

.LBB0_1310:
	s_or_b64 exec, exec, s[0:1]
	s_add_i32 s3, 0, 0x22000
	v_mov_b32_e32 v2, s3
	s_waitcnt lgkmcnt(0)
	s_barrier
	ds_read_b32 v2, v2
	s_movk_i32 s0, 0x627
	s_mov_b32 s11, 0
	s_waitcnt lgkmcnt(0)
	v_readfirstlane_b32 s26, v2
	s_nop 3
	s_and_b32 s62, s80, 7
	s_cmp_lt_u32 s26, 4
	s_cbranch_scc0 .Lqa_prompt
	s_lshl_b32 s26, s26, 3
	s_add_i32 s26, s26, s62
	s_branch .Lqa_done
.Lqa_prompt:
	s_add_i32 s63, s26, -4
	s_and_b32 s64, s62, 1
	s_lshr_b32 s65, s62, 1
	s_mov_b32 s67, 0
	s_movk_i32 s66, 45
	s_sub_i32 s59, 64, s66
	s_cmp_eq_u32 s64, 0
	s_cselect_b32 s59, s59, s66
	s_cmp_lt_u32 s63, s59
	s_cbranch_scc1 .Lqa_found
	s_sub_i32 s63, s63, s59
	s_addk_i32 s67, 0x100
	s_movk_i32 s66, 37
	s_sub_i32 s59, 64, s66
	s_cmp_eq_u32 s64, 0
	s_cselect_b32 s59, s59, s66
	s_cmp_lt_u32 s63, s59
	s_cbranch_scc1 .Lqa_found
	s_sub_i32 s63, s63, s59
	s_addk_i32 s67, 0x100
	s_movk_i32 s66, 33
	s_sub_i32 s59, 64, s66
	s_cmp_eq_u32 s64, 0
	s_cselect_b32 s59, s59, s66
	s_cmp_lt_u32 s63, s59
	s_cbranch_scc1 .Lqa_found
	s_sub_i32 s63, s63, s59
	s_addk_i32 s67, 0x100
	s_movk_i32 s66, 32
	s_sub_i32 s59, 64, s66
	s_cmp_eq_u32 s64, 0
	s_cselect_b32 s59, s59, s66
	s_cmp_lt_u32 s63, s59
	s_cbranch_scc1 .Lqa_found
	s_sub_i32 s63, s63, s59
	s_addk_i32 s67, 0x100
	s_cmp_lt_u32 s63, 0x41
	s_cbranch_scc0 .Lqa_empty
	s_lshl_b32 s63, s63, 3
	s_add_i32 s26, s63, s62
	s_addk_i32 s26, 0x420
	s_branch .Lqa_done
.Lqa_empty:
	s_movk_i32 s26, 0x7000
	s_branch .Lqa_done
.Lqa_found:
	s_sub_i32 s59, 64, s66
	s_cmp_eq_u32 s64, 0
	s_cselect_b32 s59, 0, s59
	s_add_i32 s63, s63, s59
	s_lshl_b32 s63, s63, 2
	s_or_b32 s63, s63, s65
	s_add_i32 s26, s63, s67
	s_add_i32 s26, s26, 32
.Lqa_done:
	s_cmpk_gt_i32 s26, 0x627
	s_cbranch_scc1 .LBB0_1418
	v_add_f32_e32 v2, v9, v11
	v_add_f32_e32 v3, v8, v10
	v_mul_f32_e32 v2, 0x3fb8aa3b, v2
	v_mul_f32_e32 v3, 0x3fb8aa3b, v3
	v_exp_f32_e32 v2, v2
	v_exp_f32_e32 v3, v3
	s_add_u32 s20, s86, 0x19b00000
	s_addc_u32 s21, s87, 0
	s_add_u32 s22, s86, 0x1bb40000
	v_sub_f32_e32 v2, v2, v3
	v_add_f32_e32 v186, 0x3e4ccccd, v2
	s_addc_u32 s23, s87, 0
	v_add_u32_e32 v2, -1, v6
	s_add_u32 s24, s86, 0x1e18c004
	v_cmp_lt_i32_e32 vcc, v2, v7
	s_addc_u32 s25, s87, 0
	s_add_u32 s28, s86, 0x1e18c100
	v_cndmask_b32_e32 v2, v2, v6, vcc
	v_lshlrev_b32_e32 v207, 2, v2
	v_add_u32_e32 v2, -2, v6
	s_addc_u32 s29, s87, 0
	v_cmp_lt_i32_e32 vcc, v2, v7
	s_add_u32 s36, s86, 0x13260400
	s_addc_u32 s37, s87, 0
	v_cndmask_b32_e32 v2, v2, v6, vcc
	v_lshlrev_b32_e32 v208, 2, v2
	v_add_u32_e32 v2, -4, v6
	s_add_u32 s0, s86, 0x1de80000
	v_cmp_lt_i32_e32 vcc, v2, v7
	s_addc_u32 s1, s87, 0
	s_add_u32 s94, s86, 0x1db80000
	v_cndmask_b32_e32 v2, v2, v6, vcc
	v_lshlrev_b32_e32 v209, 2, v2
	v_add_u32_e32 v2, -8, v6
	s_addc_u32 s95, s87, 0
	v_cmp_lt_i32_e32 vcc, v2, v7
	s_add_u32 s30, s86, 0x4040000
	s_addc_u32 s31, s87, 0
	v_cndmask_b32_e32 v2, v2, v6, vcc
	v_lshlrev_b32_e32 v210, 2, v2
	v_add_u32_e32 v2, -16, v6
	s_add_u32 s43, s86, 0x80c0000
	v_cmp_lt_i32_e32 vcc, v2, v7
	s_addc_u32 s50, s87, 0
	s_add_u32 s51, s86, 0x2040000
	v_cndmask_b32_e32 v2, v2, v6, vcc
	v_lshlrev_b32_e32 v211, 2, v2
	v_subrev_u32_e32 v2, 32, v6
	s_addc_u32 s81, s87, 0
	v_cmp_lt_i32_e32 vcc, v2, v7
	s_add_u32 s92, s86, 0x60c0000
	v_writelane_b32 v244, s0, 0
	v_cndmask_b32_e32 v2, v2, v6, vcc
	s_addc_u32 s93, s87, 0
	v_lshlrev_b32_e32 v212, 2, v2
	v_mov_b32_e32 v187, v186
	v_mov_b32_e32 v189, 0
	s_mov_b32 s96, 0x1020c000
	s_movk_i32 s97, 0x2000
	s_movk_i32 s78, 0x110
	s_movk_i32 s79, 0x90
	s_add_i32 s88, 0, 0x11c10
	s_mov_b32 s89, 0xc2fc0000
	s_mov_b32 s42, 0xf149f2ca
	s_mov_b32 s38, 0xf800000
	v_mov_b32_e32 v213, 0x260
	s_add_i32 s39, 0, 0x11c30
	s_movk_i32 s40, 0x80
	v_mov_b32_e32 v214, 0x358637bd
	s_mov_b32 s41, 0x800000
	s_movk_i32 s68, 0x628
	v_mov_b32_e32 v215, 0x42800000
	v_mov_b32_e32 v216, 0xf149f2ca
	v_mov_b32_e32 v217, 0x7149f2ca
	v_writelane_b32 v244, s1, 1
	s_branch .LBB0_1314

.LBB0_1313:
	v_mov_b32_e32 v2, s3
	ds_read_b32 v2, v2
	s_waitcnt lgkmcnt(0)
	v_readfirstlane_b32 s26, v2
	s_nop 3
	s_and_b32 s62, s80, 7
	s_cmp_lt_u32 s26, 4
	s_cbranch_scc0 .Lqb_prompt
	s_lshl_b32 s26, s26, 3
	s_add_i32 s26, s26, s62
	s_branch .Lqb_done

.Lqb_done:
	s_cmpk_gt_i32 s26, 0x627
	s_cbranch_scc1 .LBB0_1418

.LBB0_1375:
	s_or_b64 exec, exec, s[12:13]
	v_cndmask_b32_e64 v66, 0, 1, s[6:7]
	v_cmp_ne_u32_e64 s[0:1], 1, v66
	s_andn2_b64 vcc, exec, s[6:7]
	s_cbranch_vccnz .LBB0_1377
	s_cmp_lt_u32 s26, 4
	s_cbranch_scc1 .Latt_w1_drain
	s_waitcnt vmcnt(7)
	ds_write_b128 v195, v[98:101]
	s_waitcnt vmcnt(6)
	ds_write_b128 v195, v[102:105] offset:8704
	s_waitcnt vmcnt(5)
	ds_write_b128 v220, v[106:109] offset:17408
	s_waitcnt vmcnt(4)
	ds_write_b128 v220, v[110:113] offset:26624
	s_branch .LBB0_1377
.Latt_w1_drain:
	s_waitcnt vmcnt(3)
	ds_write_b128 v195, v[98:101]
	s_waitcnt vmcnt(2)
	ds_write_b128 v195, v[102:105] offset:8704
	s_waitcnt vmcnt(1)
	ds_write_b128 v220, v[106:109] offset:17408
	s_waitcnt vmcnt(0)
	ds_write_b128 v220, v[110:113] offset:26624
.LBB0_1377:
	s_and_b64 vcc, exec, s[0:1]
	s_waitcnt lgkmcnt(0)
	s_barrier
	s_cbranch_vccnz .LBB0_1402
	v_max_f32_e32 v66, v153, v153
	v_max_f32_e32 v67, v152, v152
	v_max_f32_e32 v66, v67, v66
	v_max3_f32 v66, v150, v151, v66
	v_mul_f32_e32 v67, 0x4f800000, v66
	v_cmp_gt_f32_e32 vcc, s38, v66
	v_max_f32_e32 v70, v148, v148
	s_add_i32 s6, s26, -6
	v_cndmask_b32_e32 v66, v66, v67, vcc
	v_sqrt_f32_e32 v67, v66
	s_mov_b32 s35, 5
	v_add_u32_e32 v68, -1, v67
	v_fma_f32 v69, -v68, v67, v66
	v_cmp_ge_f32_e64 s[0:1], 0, v69
	v_add_u32_e32 v69, 1, v67
	s_nop 0
	v_cndmask_b32_e64 v68, v67, v68, s[0:1]
	v_fma_f32 v67, -v69, v67, v66
	v_cmp_lt_f32_e64 s[0:1], 0, v67
	s_nop 1
	v_cndmask_b32_e64 v67, v68, v69, s[0:1]
	v_max_f32_e32 v69, v149, v149
	v_max_f32_e32 v69, v70, v69
	v_max3_f32 v69, v146, v147, v69
	v_mul_f32_e32 v70, 0x4f800000, v69
	v_cmp_gt_f32_e64 s[0:1], s38, v69
	v_mul_f32_e32 v68, 0x37800000, v67
	v_cndmask_b32_e32 v67, v67, v68, vcc
	v_cndmask_b32_e64 v70, v69, v70, s[0:1]
	v_sqrt_f32_e32 v69, v70
	v_cmp_class_f32_e32 vcc, v66, v213
	s_nop 1
	v_cndmask_b32_e32 v178, v67, v66, vcc
	v_add_u32_e32 v66, -1, v69
	v_fma_f32 v67, -v66, v69, v70
	v_cmp_ge_f32_e32 vcc, 0, v67
	v_add_u32_e32 v67, 1, v69
	v_fma_f32 v68, -v67, v69, v70
	v_cndmask_b32_e32 v66, v69, v66, vcc
	v_cmp_lt_f32_e32 vcc, 0, v68
	s_nop 1
	v_cndmask_b32_e32 v66, v66, v67, vcc
	v_mul_f32_e32 v67, 0x37800000, v66
	v_cndmask_b32_e64 v71, v66, v67, s[0:1]
	v_mov_b32_e32 v66, s39
	ds_read_b128 v[66:69], v66
	v_cmp_class_f32_e32 vcc, v70, v213
	s_add_i32 s0, 0, 0x11c20
	s_nop 0
	v_cndmask_b32_e32 v179, v71, v70, vcc
	v_mov_b32_e32 v70, s0
	ds_read_b128 v[70:73], v70
	s_waitcnt lgkmcnt(1)
	v_max_f32_e32 v69, v69, v69
	v_max_f32_e32 v68, v68, v68
	v_min_f32_e32 v68, v68, v69
	v_min3_f32 v67, v66, v67, v68
	s_waitcnt lgkmcnt(0)
	v_max_f32_e32 v66, v73, v73
	v_max_f32_e32 v68, v72, v72
	v_min_f32_e32 v66, v68, v66
	v_min3_f32 v66, v70, v71, v66
	s_mov_b32 s0, 0xc2200000
	v_pk_add_f32 v[180:181], v[66:67], s[0:1] op_sel_hi:[1,0]
	s_lshl_b32 s0, s26, 2
	s_add_i32 s0, s0, 0
	s_add_i32 s13, s0, 0x117e8
	s_lshl_b32 s0, s26, 6
	s_sub_i32 s12, 0, s0
	s_lshl_b32 s0, s26, 1
	s_sub_i32 s0, s71, s0
	v_mov_b32_e32 v200, v179
	s_add_i32 s34, s0, 8
	s_branch .LBB0_1380

.LBB0_1388:
	s_add_i32 s7, s35, -2
	s_cmp_lt_i32 s7, s26
	s_cselect_b64 s[0:1], -1, 0
	s_cmp_ge_i32 s7, s26
	s_cbranch_scc1 .LBB0_1390
	s_cmp_lt_i32 s46, s26
	s_cbranch_scc0 .Latt_w2_drain
	s_waitcnt vmcnt(7)
	ds_write_b128 v195, v[114:117] offset:35840
	s_waitcnt vmcnt(6)
	ds_write_b128 v195, v[118:121] offset:44544
	s_waitcnt vmcnt(5)
	ds_write_b128 v220, v[122:125] offset:53248
	s_waitcnt vmcnt(4)
	ds_write_b128 v220, v[126:129] offset:62464
	s_branch .LBB0_1390
.Latt_w2_drain:
	s_waitcnt vmcnt(3)
	ds_write_b128 v195, v[114:117] offset:35840
	s_waitcnt vmcnt(2)
	ds_write_b128 v195, v[118:121] offset:44544
	s_waitcnt vmcnt(1)
	ds_write_b128 v220, v[122:125] offset:53248
	s_waitcnt vmcnt(0)
	ds_write_b128 v220, v[126:129] offset:62464

.LBB0_1401:
	s_cmp_lt_i32 s35, s26
	s_cbranch_scc0 .Latt_w3_drain
	s_waitcnt vmcnt(7)
	ds_write_b128 v195, v[98:101]
	s_waitcnt vmcnt(6)
	ds_write_b128 v195, v[102:105] offset:8704
	s_waitcnt vmcnt(5)
	ds_write_b128 v220, v[106:109] offset:17408
	s_waitcnt vmcnt(4)
	ds_write_b128 v220, v[110:113] offset:26624
	s_branch .LBB0_1379

.LBB0_1418:
	s_setprio 0
	s_cmp_lt_i32 s15, 8
	s_cbranch_scc1 .LBB0_1472
	s_waitcnt vmcnt(0)
	s_barrier
	s_and_saveexec_b64 s[0:1], s[82:83]
	s_cbranch_execz .LBB0_1471
	s_add_i32 s3, 0, 0x22010
	v_mov_b32_e32 v1, s3
	s_waitcnt vmcnt(0) expcnt(0) lgkmcnt(0)
	ds_read_b32 v3, v1
	s_add_i32 s3, 0, 0x22014
	v_mov_b32_e32 v1, s3
	ds_read_b32 v1, v1
	s_waitcnt lgkmcnt(1)
	v_cmp_ne_u32_e32 vcc, 0, v3
	s_cbranch_vccnz .LBB0_1435
	v_readlane_b32 s4, v244, 34
	v_readlane_b32 s5, v244, 35
	s_load_dwordx2 s[8:9], s[4:5], 0x4
	s_add_u32 s4, s86, 0x1e28c300
	s_addc_u32 s5, s87, 0
	s_add_u32 s6, s86, 0x1e28c500
	s_addc_u32 s7, s87, 0
	s_waitcnt lgkmcnt(0)
	s_mul_i32 s3, s8, s33
	s_add_u32 s8, s86, 0x1e28c600
	s_mul_i32 s3, s3, s9
	s_addc_u32 s9, s87, 0
	s_add_u32 s10, s86, 0x1e28c700
	s_addc_u32 s11, s87, 0
	s_add_u32 s20, s86, 0x1e28c800
	s_addc_u32 s21, s87, 0
	s_add_u32 s22, s86, 0x1e28c900
	s_addc_u32 s23, s87, 0
	s_add_u32 s24, s86, 0x1e28ca00
	s_addc_u32 s25, s87, 0
	s_add_u32 s34, s86, 0x1e28cb00
	s_addc_u32 s35, s87, 0
	s_add_u32 s36, s86, 0x1e28cc00
	s_addc_u32 s37, s87, 0
	s_add_u32 s38, s86, 0x1e28cd00
	s_addc_u32 s39, s87, 0
	s_add_u32 s40, s86, 0x1e28ce00
	s_addc_u32 s41, s87, 0
	s_add_u32 s42, s86, 0x1e28cf00
	s_addc_u32 s43, s87, 0
	s_add_u32 s44, s86, 0x1e28d000
	s_addc_u32 s45, s87, 0
	s_add_u32 s46, s86, 0x1e28d100
	s_addc_u32 s47, s87, 0
	s_add_u32 s48, s86, 0x1e28d200
	s_addc_u32 s49, s87, 0
	s_add_u32 s50, s86, 0x1e28d300
	s_addc_u32 s51, s87, 0
	s_add_u32 s52, s86, 0x1e28d400
	s_addc_u32 s53, s87, 0
	s_mov_b32 s30, 1
	v_mov_b32_e32 v17, 0
	s_branch .LBB0_1423
